# thin stage 3: both SSS row-partial loads issued before the last MFMA pair and barrier instead of one after the other behind it
# baseline (speedup 1.0000x reference)
.LBB0_1066:
	s_mul_hi_i32 s3, s2, 0x2e8ba2e9
	s_lshr_b32 s8, s3, 31
	s_ashr_i32 s3, s3, 5
	s_add_i32 s3, s3, s8
	s_mul_i32 s8, s3, 0xb0
	s_sub_i32 s8, s2, s8
	s_lshl_b32 s2, s3, 6
	s_add_i32 s10, s2, 0x8000
	s_ashr_i32 s11, s10, 31
	s_lshl_b32 s14, s8, 4
	s_lshl_b32 s3, s8, 5
	s_lshl_b64 s[20:21], s[10:11], 11
	s_and_b32 s3, s3, 0xffffff00
	s_and_b32 s8, s14, 0x70
	v_lshl_add_u64 v[114:115], v[2:3], 0, s[20:21]
	s_or_b32 s8, s3, s8
	v_add_co_u32_e32 v118, vcc, s4, v114
	s_ashr_i32 s9, s8, 31
	s_nop 0
	v_addc_co_u32_e32 v119, vcc, 0, v115, vcc
	s_lshl_b64 s[22:23], s[8:9], 11
	s_bitset1_b32 s8, 7
	v_add_co_u32_e32 v122, vcc, s5, v114
	s_ashr_i32 s9, s8, 31
	s_nop 0
	v_addc_co_u32_e32 v123, vcc, 0, v115, vcc
	s_lshl_b64 s[8:9], s[8:9], 11
	v_add_co_u32_e32 v130, vcc, s16, v114
	v_lshl_add_u64 v[98:99], v[4:5], 0, s[22:23]
	v_lshl_add_u64 v[116:117], v[4:5], 0, s[8:9]
	v_addc_co_u32_e32 v131, vcc, 0, v115, vcc
	global_load_dwordx4 v[38:41], v[98:99], off
	global_load_dwordx4 v[42:45], v[98:99], off offset:64
	global_load_dwordx4 v[46:49], v[116:117], off
	global_load_dwordx4 v[50:53], v[116:117], off offset:64
	global_load_dwordx4 v[54:57], v[114:115], off
	global_load_dwordx4 v[58:61], v[114:115], off offset:64
	global_load_dwordx4 v[62:65], v[118:119], off
	global_load_dwordx4 v[66:69], v[118:119], off offset:64
	global_load_dwordx4 v[70:73], v[122:123], off
	global_load_dwordx4 v[74:77], v[122:123], off offset:64
	global_load_dwordx4 v[78:81], v[130:131], off
	global_load_dwordx4 v[82:85], v[130:131], off offset:64
	global_load_dwordx4 v[86:89], v[98:99], off offset:128
	global_load_dwordx4 v[90:93], v[98:99], off offset:192
	global_load_dwordx4 v[94:97], v[116:117], off offset:128
	s_nop 0
	global_load_dwordx4 v[98:101], v[116:117], off offset:192
	global_load_dwordx4 v[102:105], v[114:115], off offset:128
	global_load_dwordx4 v[106:109], v[114:115], off offset:192
	global_load_dwordx4 v[110:113], v[118:119], off offset:128
	s_nop 0
	global_load_dwordx4 v[114:117], v[118:119], off offset:192
	s_nop 0
	global_load_dwordx4 v[118:121], v[122:123], off offset:128
	s_nop 0
	global_load_dwordx4 v[122:125], v[122:123], off offset:192
	s_nop 0
	global_load_dwordx4 v[126:129], v[130:131], off offset:128
	s_nop 0
	global_load_dwordx4 v[130:133], v[130:131], off offset:192
	s_xor_b64 s[8:9], s[12:13], -1
	s_waitcnt vmcnt(19)
	v_mfma_f32_16x16x32_bf16 v[134:137], v[54:57], v[38:41], 0
	s_ashr_i32 s15, s14, 31
	v_mfma_f32_16x16x32_bf16 v[54:57], v[54:57], v[46:49], 0
	s_waitcnt vmcnt(17)
	v_mfma_f32_16x16x32_bf16 v[138:141], v[62:65], v[38:41], 0
	v_mfma_f32_16x16x32_bf16 v[62:65], v[62:65], v[46:49], 0
	s_waitcnt vmcnt(15)
	v_mfma_f32_16x16x32_bf16 v[142:145], v[70:73], v[38:41], 0
	v_mfma_f32_16x16x32_bf16 v[70:73], v[70:73], v[46:49], 0
	s_waitcnt vmcnt(13)
	v_mfma_f32_16x16x32_bf16 v[38:41], v[78:81], v[38:41], 0
	v_mfma_f32_16x16x32_bf16 v[46:49], v[78:81], v[46:49], 0
	v_mfma_f32_16x16x32_bf16 v[78:81], v[58:61], v[42:45], v[134:137]
	v_mfma_f32_16x16x32_bf16 v[54:57], v[58:61], v[50:53], v[54:57]
	v_mfma_f32_16x16x32_bf16 v[58:61], v[66:69], v[42:45], v[138:141]
	v_mfma_f32_16x16x32_bf16 v[62:65], v[66:69], v[50:53], v[62:65]
	v_mfma_f32_16x16x32_bf16 v[66:69], v[74:77], v[42:45], v[142:145]
	v_mfma_f32_16x16x32_bf16 v[70:73], v[74:77], v[50:53], v[70:73]
	s_waitcnt vmcnt(12)
	v_mfma_f32_16x16x32_bf16 v[38:41], v[82:85], v[42:45], v[38:41]
	v_mfma_f32_16x16x32_bf16 v[42:45], v[82:85], v[50:53], v[46:49]
	s_waitcnt vmcnt(7)
	v_mfma_f32_16x16x32_bf16 v[46:49], v[102:105], v[86:89], v[78:81]
	v_mfma_f32_16x16x32_bf16 v[50:53], v[102:105], v[94:97], v[54:57]
	s_waitcnt vmcnt(5)
	v_mfma_f32_16x16x32_bf16 v[54:57], v[110:113], v[86:89], v[58:61]
	v_mfma_f32_16x16x32_bf16 v[58:61], v[110:113], v[94:97], v[62:65]
	s_waitcnt vmcnt(3)
	v_mfma_f32_16x16x32_bf16 v[62:65], v[118:121], v[86:89], v[66:69]
	v_mfma_f32_16x16x32_bf16 v[66:69], v[118:121], v[94:97], v[70:73]
	s_waitcnt vmcnt(1)
	v_mfma_f32_16x16x32_bf16 v[38:41], v[126:129], v[86:89], v[38:41]
	v_mfma_f32_16x16x32_bf16 v[42:45], v[126:129], v[94:97], v[42:45]
	v_mfma_f32_16x16x32_bf16 v[46:49], v[106:109], v[90:93], v[46:49]
	v_mfma_f32_16x16x32_bf16 v[50:53], v[106:109], v[98:101], v[50:53]
	s_nop 7
	ds_write2_b32 v18, v46, v50 offset1:16
	ds_write2_b32 v18, v47, v51 offset0:32 offset1:48
	ds_write2_b32 v18, v48, v52 offset0:64 offset1:80
	v_mfma_f32_16x16x32_bf16 v[54:57], v[114:117], v[90:93], v[54:57]
	v_mfma_f32_16x16x32_bf16 v[58:61], v[114:117], v[98:101], v[58:61]
	ds_write2_b32 v18, v49, v53 offset0:96 offset1:112
	s_nop 6
	ds_write2_b32 v20, v54, v58 offset1:16
	ds_write2_b32 v20, v55, v59 offset0:32 offset1:48
	v_mfma_f32_16x16x32_bf16 v[62:65], v[122:125], v[90:93], v[62:65]
	v_mfma_f32_16x16x32_bf16 v[46:49], v[122:125], v[98:101], v[66:69]
	ds_write2_b32 v20, v56, v60 offset0:64 offset1:80
	ds_write2_b32 v20, v57, v61 offset0:96 offset1:112
	s_nop 5
	ds_write2_b32 v21, v62, v46 offset1:16
	ds_write2_b32 v21, v63, v47 offset0:32 offset1:48
	ds_write2_b32 v21, v64, v48 offset0:64 offset1:80
	ds_write2_b32 v21, v65, v49 offset0:96 offset1:112
	s_waitcnt vmcnt(0)
	v_or_b32_e32 v244, s2, v1
	v_ashrrev_i32_e32 v245, 31, v244
	v_lshlrev_b64 v[244:245], 8, v[244:245]
	v_lshl_add_u64 v[244:245], v[6:7], 0, v[244:245]
	global_load_dwordx4 v[248:251], v[244:245], off
	v_or_b32_e32 v244, s2, v12
	v_ashrrev_i32_e32 v245, 31, v244
	v_lshlrev_b64 v[244:245], 8, v[244:245]
	v_lshl_add_u64 v[244:245], v[6:7], 0, v[244:245]
	global_load_dwordx4 v[252:255], v[244:245], off
	v_mfma_f32_16x16x32_bf16 v[38:41], v[130:133], v[90:93], v[38:41]
	v_or_b32_e32 v56, s10, v1
	v_mfma_f32_16x16x32_bf16 v[42:45], v[130:133], v[98:101], v[42:45]
	s_nop 7
	ds_write2_b32 v22, v38, v42 offset1:16
	ds_write2_b32 v22, v39, v43 offset0:32 offset1:48
	ds_write2_b32 v22, v40, v44 offset0:64 offset1:80
	ds_write2_b32 v22, v41, v45 offset0:96 offset1:112
	v_or_b32_e32 v38, s2, v1
	v_ashrrev_i32_e32 v39, 31, v38
	v_lshlrev_b64 v[38:39], 8, v[38:39]
	v_lshl_add_u64 v[38:39], v[6:7], 0, v[38:39]
	s_waitcnt lgkmcnt(0)
	s_barrier
	s_waitcnt vmcnt(0)
	v_mov_b64_e32 v[38:39], v[248:249]
	v_mov_b64_e32 v[40:41], v[250:251]
	v_lshl_add_u64 v[42:43], s[14:15], 1, v[8:9]
	s_waitcnt vmcnt(0)
	v_add_f32_e32 v37, v38, v39
	v_add_f32_e32 v38, v40, v41
	v_add_f32_e32 v37, v37, v38
	ds_bpermute_b32 v38, v14, v37
	s_waitcnt lgkmcnt(0)
	v_add_f32_e32 v37, v37, v38
	ds_bpermute_b32 v38, v15, v37
	s_waitcnt lgkmcnt(0)
	v_add_f32_e32 v37, v37, v38
	ds_bpermute_b32 v38, v16, v37
	s_waitcnt lgkmcnt(0)
	v_add_f32_e32 v37, v37, v38
	ds_bpermute_b32 v38, v17, v37
	s_waitcnt lgkmcnt(0)
	v_add_f32_e32 v37, v37, v38
	ds_read2_b32 v[38:39], v11 offset1:16
	ds_read2_b32 v[40:41], v23 offset1:16
	ds_read2_b32 v[44:45], v24 offset1:16
	ds_read2_b32 v[46:47], v25 offset1:16
	ds_read2_b32 v[48:49], v26 offset1:16
	ds_read2_b32 v[50:51], v27 offset1:16
	ds_read2_b32 v[52:53], v28 offset1:16
	ds_read2_b32 v[54:55], v29 offset1:16
	v_fmamk_f32 v37, v37, 0x3a800000, v19
	s_waitcnt lgkmcnt(7)
	v_add_f32_e32 v38, 0, v38
	s_waitcnt lgkmcnt(6)
	v_add_f32_e32 v38, v38, v40
	s_waitcnt lgkmcnt(5)
	v_add_f32_e32 v38, v38, v44
	s_waitcnt lgkmcnt(4)
	v_add_f32_e32 v38, v38, v46
	v_rsq_f32_e32 v37, v37
	s_waitcnt lgkmcnt(3)
	v_add_f32_e32 v38, v38, v48
	s_waitcnt lgkmcnt(2)
	v_add_f32_e32 v38, v38, v50
	s_waitcnt lgkmcnt(1)
	v_add_f32_e32 v38, v38, v52
	s_waitcnt lgkmcnt(0)
	v_add_f32_e32 v44, v38, v54
	v_mul_f32_e32 v44, v37, v44
	v_mul_f32_e32 v46, 0xbfb8aa3b, v44
	v_exp_f32_e32 v46, v46
	v_add_f32_e32 v38, 0, v39
	v_add_f32_e32 v38, v38, v41
	v_add_f32_e32 v45, v38, v45
	v_add_f32_e32 v45, v45, v47
	v_add_f32_e32 v46, 1.0, v46
	v_add_f32_e32 v45, v45, v49
	v_rcp_f32_e32 v46, v46
	v_add_f32_e32 v45, v45, v51
	v_add_f32_e32 v45, v45, v53
	v_add_f32_e32 v45, v45, v55
	v_mul_f32_e32 v37, v37, v45
	v_mul_f32_e32 v44, v44, v46
	v_or_b32_e32 v40, s2, v12
	v_mul_f32_e32 v37, v44, v37
	v_ashrrev_i32_e32 v41, 31, v40
	v_bfe_u32 v44, v37, 16, 1
	v_mad_i64_i32 v[38:39], s[12:13], v56, s18, v[42:43]
	v_lshlrev_b64 v[40:41], 8, v[40:41]
	v_add3_u32 v37, v37, v44, s17
	v_lshl_add_u64 v[40:41], v[6:7], 0, v[40:41]
	global_store_short_d16_hi v[38:39], v37, off
	v_mov_b64_e32 v[38:39], v[252:253]
	v_mov_b64_e32 v[40:41], v[254:255]
	v_or_b32_e32 v37, s10, v12
	v_mad_i64_i32 v[42:43], s[2:3], v37, s18, v[42:43]
	s_nop 0
	v_add_f32_e32 v37, v38, v39
	v_add_f32_e32 v38, v40, v41
	v_add_f32_e32 v37, v37, v38
	ds_bpermute_b32 v48, v14, v37
	ds_read2_b32 v[38:39], v13 offset1:16
	ds_read2_b32 v[40:41], v30 offset1:16
	ds_read2_b32 v[44:45], v31 offset1:16
	ds_read2_b32 v[46:47], v32 offset1:16
	s_waitcnt lgkmcnt(3)
	v_add_f32_e32 v38, 0, v38
	s_waitcnt lgkmcnt(2)
	v_add_f32_e32 v38, v38, v40
	v_add_f32_e32 v37, v37, v48
	ds_bpermute_b32 v56, v15, v37
	ds_read2_b32 v[48:49], v33 offset1:16
	ds_read2_b32 v[50:51], v34 offset1:16
	ds_read2_b32 v[52:53], v35 offset1:16
	ds_read2_b32 v[54:55], v36 offset1:16
	s_waitcnt lgkmcnt(6)
	v_add_f32_e32 v38, v38, v44
	s_waitcnt lgkmcnt(5)
	v_add_f32_e32 v38, v38, v46
	s_waitcnt lgkmcnt(3)
	v_add_f32_e32 v38, v38, v48
	v_add_f32_e32 v37, v37, v56
	ds_bpermute_b32 v56, v16, v37
	s_waitcnt lgkmcnt(3)
	v_add_f32_e32 v38, v38, v50
	s_waitcnt lgkmcnt(2)
	v_add_f32_e32 v38, v38, v52
	s_waitcnt lgkmcnt(1)
	v_add_f32_e32 v38, v38, v54
	v_add_f32_e32 v39, 0, v39
	s_waitcnt lgkmcnt(0)
	v_add_f32_e32 v37, v37, v56
	ds_bpermute_b32 v40, v17, v37
	v_add_f32_e32 v39, v39, v41
	v_add_f32_e32 v39, v39, v45
	v_add_f32_e32 v39, v39, v47
	v_add_f32_e32 v39, v39, v49
	s_waitcnt lgkmcnt(0)
	v_add_f32_e32 v37, v37, v40
	v_fmamk_f32 v37, v37, 0x3a800000, v19
	v_rsq_f32_e32 v37, v37
	v_add_f32_e32 v39, v39, v51
	v_add_f32_e32 v39, v39, v53
	v_add_f32_e32 v39, v39, v55
	v_mul_f32_e32 v38, v37, v38
	v_mul_f32_e32 v40, 0xbfb8aa3b, v38
	v_exp_f32_e32 v40, v40
	v_mul_f32_e32 v37, v37, v39
	v_add_f32_e32 v40, 1.0, v40
	v_rcp_f32_e32 v40, v40
	s_nop 0
	v_mul_f32_e32 v38, v38, v40
	v_mul_f32_e32 v37, v38, v37
	v_bfe_u32 v38, v37, 16, 1
	v_add3_u32 v37, v37, v38, s17
	global_store_short_d16_hi v[42:43], v37, off
	s_barrier
	s_branch .LBB0_1060
